# v011 + attention near-diagonal tiles: unclamped unmasked bias lookup via one base + immediate offsets
# baseline (speedup 1.0000x reference)
.LBB0_2765:
	s_andn2_b64 vcc, exec, s[8:9]
	s_cbranch_vccnz .LBB0_2775
	s_and_b32 s22, s21, 0x8000
	v_ashrrev_i32_e32 v16, 5, v242
	v_and_b32_e32 v2, 31, v242
	s_add_i32 s8, s43, s22
	v_lshlrev_b32_e32 v17, 4, v16
	v_lshlrev_b32_e32 v253, 4, v242
	v_and_b32_e32 v158, 0x70, v253
	v_lshl_add_u32 v159, v2, 8, s8
	v_add_u32_e32 v12, 32, v17
	v_xad_u32 v8, v17, v158, v159
	v_xad_u32 v146, v12, v158, v159
	ds_read_b128 v[4:7], v8
	ds_read_b128 v[8:11], v8 offset:8192
	ds_read_b128 v[12:15], v146
	ds_read_b128 v[146:149], v146 offset:8192
	v_add_u32_e32 v150, 64, v17
	v_xad_u32 v154, v150, v158, v159
	ds_read_b128 v[150:153], v154
	ds_read_b128 v[154:157], v154 offset:8192
	s_waitcnt lgkmcnt(0)
	v_mfma_f32_32x32x16_bf16 v[178:193], v[4:7], v[210:213], 0
	v_mfma_f32_32x32x16_bf16 v[194:209], v[8:11], v[210:213], 0
	v_add_u32_e32 v4, 0x60, v17
	v_xad_u32 v8, v4, v158, v159
	ds_read_b128 v[4:7], v8
	ds_read_b128 v[8:11], v8 offset:8192
	v_mfma_f32_32x32x16_bf16 v[178:193], v[12:15], v[214:217], v[178:193]
	v_mfma_f32_32x32x16_bf16 v[194:209], v[146:149], v[214:217], v[194:209]
	v_add_u32_e32 v12, 0x80, v17
	v_xad_u32 v146, v12, v158, v159
	ds_read_b128 v[12:15], v146
	ds_read_b128 v[146:149], v146 offset:8192
	v_mfma_f32_32x32x16_bf16 v[178:193], v[150:153], v[218:221], v[178:193]
	v_mfma_f32_32x32x16_bf16 v[194:209], v[154:157], v[218:221], v[194:209]
	v_add_u32_e32 v150, 0xa0, v17
	v_xad_u32 v154, v150, v158, v159
	ds_read_b128 v[150:153], v154
	ds_read_b128 v[154:157], v154 offset:8192
	s_waitcnt lgkmcnt(0)
	v_mfma_f32_32x32x16_bf16 v[178:193], v[4:7], v[222:225], v[178:193]
	v_mfma_f32_32x32x16_bf16 v[194:209], v[8:11], v[222:225], v[194:209]
	v_add_u32_e32 v4, 0xc0, v17
	v_xad_u32 v8, v4, v158, v159
	ds_read_b128 v[4:7], v8
	ds_read_b128 v[8:11], v8 offset:8192
	v_mfma_f32_32x32x16_bf16 v[178:193], v[12:15], v[226:229], v[178:193]
	v_mfma_f32_32x32x16_bf16 v[194:209], v[146:149], v[226:229], v[194:209]
	v_add_u32_e32 v12, 0xe0, v17
	v_xad_u32 v17, v12, v158, v159
	ds_read_b128 v[12:15], v17
	ds_read_b128 v[146:149], v17 offset:8192
	v_mfma_f32_32x32x16_bf16 v[178:193], v[150:153], v[230:233], v[178:193]
	v_mfma_f32_32x32x16_bf16 v[194:209], v[154:157], v[230:233], v[194:209]
	s_waitcnt lgkmcnt(0)
	v_mfma_f32_32x32x16_bf16 v[178:193], v[4:7], v[234:237], v[178:193]
	v_mfma_f32_32x32x16_bf16 v[194:209], v[8:11], v[234:237], v[194:209]
	v_mfma_f32_32x32x16_bf16 v[178:193], v[12:15], v[238:241], v[178:193]
	v_mfma_f32_32x32x16_bf16 v[194:209], v[146:149], v[238:241], v[194:209]
	s_add_i32 s23, s18, s20
	s_add_i32 s10, s20, 63
	s_add_i32 s8, s23, 0xffffe0bf
	s_cmpk_lt_i32 s8, 0xffa6
	s_cselect_b64 s[8:9], -1, 0
	s_cmp_lt_i32 s10, s15
	s_cselect_b64 s[12:13], -1, 0
	s_and_b64 s[10:11], s[12:13], s[8:9]
	s_mov_b64 s[8:9], -1
	s_and_b64 vcc, exec, s[10:11]
	v_lshlrev_b32_e32 v11, 2, v16
	s_cbranch_vccnz .LBB0_2768
	v_sub_u32_e32 v2, v11, v2
	v_add_u32_e32 v2, s23, v2
	s_add_i32 s23, 0, 0x18600
	v_lshl_add_u32 v2, v2, 2, s23
	ds_read2_b32 v[162:163], v2 offset0:0 offset1:1
	ds_read2_b32 v[164:165], v2 offset0:2 offset1:3
	ds_read2_b32 v[166:167], v2 offset0:8 offset1:9
	ds_read2_b32 v[168:169], v2 offset0:10 offset1:11
	ds_read2_b32 v[170:171], v2 offset0:16 offset1:17
	ds_read2_b32 v[172:173], v2 offset0:18 offset1:19
	ds_read2_b32 v[174:175], v2 offset0:24 offset1:25
	ds_read2_b32 v[176:177], v2 offset0:26 offset1:27
	ds_read2_b32 v[146:147], v2 offset0:32 offset1:33
	ds_read2_b32 v[148:149], v2 offset0:34 offset1:35
	ds_read2_b32 v[150:151], v2 offset0:40 offset1:41
	ds_read2_b32 v[152:153], v2 offset0:42 offset1:43
	ds_read2_b32 v[154:155], v2 offset0:48 offset1:49
	ds_read2_b32 v[156:157], v2 offset0:50 offset1:51
	ds_read2_b32 v[158:159], v2 offset0:56 offset1:57
	ds_read2_b32 v[160:161], v2 offset0:58 offset1:59
	s_waitcnt lgkmcnt(0)
	v_fmac_f32_e32 v162, 0x3e0293ee, v178
	v_fmac_f32_e32 v146, 0x3e0293ee, v194
	v_fmac_f32_e32 v163, 0x3e0293ee, v179
	v_fmac_f32_e32 v147, 0x3e0293ee, v195
	v_max_f32_e32 v2, v162, v146
	v_fmac_f32_e32 v164, 0x3e0293ee, v180
	v_fmac_f32_e32 v148, 0x3e0293ee, v196
	v_max3_f32 v2, v2, v163, v147
	v_fmac_f32_e32 v165, 0x3e0293ee, v181
	v_fmac_f32_e32 v149, 0x3e0293ee, v197
	v_max3_f32 v2, v2, v164, v148
	v_fmac_f32_e32 v166, 0x3e0293ee, v182
	v_fmac_f32_e32 v150, 0x3e0293ee, v198
	v_max3_f32 v2, v2, v165, v149
	v_fmac_f32_e32 v167, 0x3e0293ee, v183
	v_fmac_f32_e32 v151, 0x3e0293ee, v199
	v_max3_f32 v2, v2, v166, v150
	v_fmac_f32_e32 v168, 0x3e0293ee, v184
	v_fmac_f32_e32 v152, 0x3e0293ee, v200
	v_max3_f32 v2, v2, v167, v151
	v_fmac_f32_e32 v169, 0x3e0293ee, v185
	v_fmac_f32_e32 v153, 0x3e0293ee, v201
	v_max3_f32 v2, v2, v168, v152
	v_fmac_f32_e32 v170, 0x3e0293ee, v186
	v_fmac_f32_e32 v154, 0x3e0293ee, v202
	v_max3_f32 v2, v2, v169, v153
	v_fmac_f32_e32 v171, 0x3e0293ee, v187
	v_fmac_f32_e32 v155, 0x3e0293ee, v203
	v_max3_f32 v2, v2, v170, v154
	v_fmac_f32_e32 v172, 0x3e0293ee, v188
	v_fmac_f32_e32 v156, 0x3e0293ee, v204
	v_max3_f32 v2, v2, v171, v155
	v_fmac_f32_e32 v173, 0x3e0293ee, v189
	v_fmac_f32_e32 v157, 0x3e0293ee, v205
	v_max3_f32 v2, v2, v172, v156
	v_fmac_f32_e32 v174, 0x3e0293ee, v190
	v_fmac_f32_e32 v158, 0x3e0293ee, v206
	v_max3_f32 v2, v2, v173, v157
	v_fmac_f32_e32 v175, 0x3e0293ee, v191
	v_fmac_f32_e32 v159, 0x3e0293ee, v207
	v_max3_f32 v2, v2, v174, v158
	v_fmac_f32_e32 v176, 0x3e0293ee, v192
	v_fmac_f32_e32 v160, 0x3e0293ee, v208
	v_max3_f32 v2, v2, v175, v159
	v_fmac_f32_e32 v177, 0x3e0293ee, v193
	v_fmac_f32_e32 v161, 0x3e0293ee, v209
	v_max3_f32 v2, v2, v176, v160
	v_max3_f32 v4, v2, v177, v161
	s_mov_b64 s[8:9], 0
